# attention KV loop: back edge rotated to one conditional branch; 0+x seed adds of two row-sum chains dropped
# baseline (speedup 1.0000x reference)
.LBB0_400:
	v_cvt_pk_bf16_f32 v182, v148, v149
	v_cvt_pk_bf16_f32 v183, v152, v153
	v_cvt_pk_bf16_f32 v184, v154, v155
	v_cvt_pk_bf16_f32 v185, v158, v159
	v_cvt_pk_bf16_f32 v160, v150, v151
	v_cvt_pk_bf16_f32 v161, v156, v157
	v_cvt_pk_bf16_f32 v162, v162, v163
	v_cvt_pk_bf16_f32 v163, v166, v167
	s_cmpk_lt_u32 s51, 0x100
	s_cselect_b32 s0, s38, s34
	s_add_i32 s3, s0, s51
	s_mul_i32 s0, s3, 0x1800
	s_mul_hi_i32 s1, s3, 0x1800
	s_add_u32 s0, s39, s0
	s_addc_u32 s1, s42, s1
	s_max_i32 vcc_lo, s100, 0
	s_add_i32 vcc_lo, vcc_lo, s96
	s_add_i32 m0, vcc_lo, 0x4100
	s_nop 0
	global_load_lds_dwordx4 v129, s[0:1]
	s_add_i32 m0, vcc_lo, 0x4500
	s_nop 0
	global_load_lds_dwordx4 v130, s[0:1]
	s_mul_i32 s0, s3, 0x1800
	s_mul_hi_i32 s1, s3, 0x1800
	s_add_u32 s0, s28, s0
	s_addc_u32 s1, s29, s1
	s_max_i32 vcc_lo, s101, 0
	s_add_i32 vcc_lo, vcc_lo, s97
	s_add_i32 m0, vcc_lo, 0xa100
	s_nop 0
	global_load_lds_dwordx4 v128, s[0:1]
	ds_read_b64_tr_b16 v[186:187], v203 offset:0
	ds_read_b64_tr_b16 v[188:189], v203 offset:0x800
	ds_read_b64_tr_b16 v[214:215], v203 offset:0x200
	ds_read_b64_tr_b16 v[216:217], v203 offset:0xa00
	ds_read_b64_tr_b16 v[218:219], v203 offset:0x400
	ds_read_b64_tr_b16 v[220:221], v203 offset:0xc00
	ds_read_b64_tr_b16 v[222:223], v203 offset:0x600
	ds_read_b64_tr_b16 v[224:225], v203 offset:0xe00
	ds_read_b64_tr_b16 v[226:227], v203 offset:0x1000
	ds_read_b64_tr_b16 v[228:229], v203 offset:0x1800
	ds_read_b64_tr_b16 v[230:231], v203 offset:0x1200
	ds_read_b64_tr_b16 v[232:233], v203 offset:0x1a00
	ds_read_b64_tr_b16 v[234:235], v203 offset:0x1400
	ds_read_b64_tr_b16 v[236:237], v203 offset:0x1c00
	ds_read_b64_tr_b16 v[238:239], v203 offset:0x1600
	ds_read_b64_tr_b16 v[240:241], v203 offset:0x1e00
	s_nop 0
	s_waitcnt lgkmcnt(8)
	v_exp_f32_e32 v112, v112
	v_mfma_f32_32x32x16_bf16 v[0:15], v[144:147], v[186:189], v[0:15]
	v_exp_f32_e32 v113, v113
	v_exp_f32_e32 v114, v114
	v_exp_f32_e32 v115, v115
	v_exp_f32_e32 v116, v116
	v_exp_f32_e32 v117, v117
	v_exp_f32_e32 v118, v118
	v_exp_f32_e32 v119, v119
	v_mfma_f32_32x32x16_bf16 v[48:63], v[144:147], v[214:217], v[48:63]
	v_exp_f32_e32 v120, v120
	v_exp_f32_e32 v121, v121
	v_exp_f32_e32 v122, v122
	v_exp_f32_e32 v123, v123
	v_exp_f32_e32 v124, v124
	v_exp_f32_e32 v125, v125
	v_exp_f32_e32 v126, v126
	v_mfma_f32_32x32x16_bf16 v[32:47], v[144:147], v[218:221], v[32:47]
	v_exp_f32_e32 v127, v127
	v_mfma_f32_32x32x16_bf16 v[16:31], v[144:147], v[222:225], v[16:31]
	ds_read_b64_tr_b16 v[144:145], v203 offset:0x2000
	ds_read_b64_tr_b16 v[146:147], v203 offset:0x2800
	ds_read_b64_tr_b16 v[186:187], v203 offset:0x2200
	ds_read_b64_tr_b16 v[188:189], v203 offset:0x2a00
	ds_read_b64_tr_b16 v[214:215], v203 offset:0x2400
	ds_read_b64_tr_b16 v[216:217], v203 offset:0x2c00
	ds_read_b64_tr_b16 v[218:219], v203 offset:0x2600
	ds_read_b64_tr_b16 v[220:221], v203 offset:0x2e00
	s_waitcnt lgkmcnt(8)
	ds_read_b64_tr_b16 v[222:223], v203 offset:0x3000
	ds_read_b64_tr_b16 v[224:225], v203 offset:0x3800
	s_nop 0
	v_mfma_f32_32x32x16_bf16 v[0:15], v[140:143], v[226:229], v[0:15]
	ds_read_b64_tr_b16 v[226:227], v203 offset:0x3200
	ds_read_b64_tr_b16 v[228:229], v203 offset:0x3a00
	v_mfma_f32_32x32x16_bf16 v[48:63], v[140:143], v[230:233], v[48:63]
	ds_read_b64_tr_b16 v[230:231], v203 offset:0x3400
	ds_read_b64_tr_b16 v[232:233], v203 offset:0x3c00
	v_mfma_f32_32x32x16_bf16 v[32:47], v[140:143], v[234:237], v[32:47]
	ds_read_b64_tr_b16 v[234:235], v203 offset:0x3600
	ds_read_b64_tr_b16 v[236:237], v203 offset:0x3e00
	s_waitcnt lgkmcnt(8)
	s_nop 0
	s_waitcnt lgkmcnt(0)
	v_mfma_f32_32x32x16_bf16 v[16:31], v[140:143], v[238:241], v[16:31]
	v_add_f32_e32 v140, v113, v112
	v_add_f32_e32 v140, v114, v140
	v_add_f32_e32 v140, v115, v140
	v_add_f32_e32 v140, v116, v140
	v_add_f32_e32 v140, v117, v140
	v_add_f32_e32 v140, v118, v140
	v_mfma_f32_32x32x16_bf16 v[0:15], v[182:185], v[144:147], v[0:15]
	v_add_f32_e32 v140, v119, v140
	v_add_f32_e32 v140, v120, v140
	v_add_f32_e32 v140, v121, v140
	v_add_f32_e32 v140, v122, v140
	v_add_f32_e32 v140, v123, v140
	v_add_f32_e32 v140, v124, v140
	v_add_f32_e32 v140, v125, v140
	v_mfma_f32_32x32x16_bf16 v[48:63], v[182:185], v[186:189], v[48:63]
	v_add_f32_e32 v140, v126, v140
	v_add_f32_e32 v165, v127, v140
	v_cvt_pk_bf16_f32 v144, v112, v113
	v_cvt_pk_bf16_f32 v145, v114, v115
	v_cvt_pk_bf16_f32 v146, v116, v117
	v_cvt_pk_bf16_f32 v147, v118, v119
	v_cvt_pk_bf16_f32 v140, v120, v121
	v_mfma_f32_32x32x16_bf16 v[32:47], v[182:185], v[214:217], v[32:47]
	v_cvt_pk_bf16_f32 v141, v122, v123
	v_cvt_pk_bf16_f32 v142, v124, v125
	v_cvt_pk_bf16_f32 v143, v126, v127
	v_mfma_f32_32x32x16_bf16 v[16:31], v[182:185], v[218:221], v[16:31]
	v_add_u32_e32 v208, s101, v208
	v_add_u32_e32 v209, s101, v209
	v_add_u32_e32 v210, s101, v210
	v_add_u32_e32 v211, s101, v211
	s_waitcnt vmcnt(3)
	s_waitcnt lgkmcnt(0)
	s_barrier
	v_mfma_f32_32x32x16_bf16 v[0:15], v[160:163], v[222:225], v[0:15]
	v_mfma_f32_32x32x16_bf16 v[48:63], v[160:163], v[226:229], v[48:63]
	v_mfma_f32_32x32x16_bf16 v[32:47], v[160:163], v[230:233], v[32:47]
	v_mfma_f32_32x32x16_bf16 v[16:31], v[160:163], v[234:237], v[16:31]
	ds_read_b128 v[160:163], v208 offset:32768
	ds_read_b128 v[222:225], v208 offset:36864
	v_exp_f32_e32 v166, v84
	v_exp_f32_e32 v167, v85
	s_waitcnt lgkmcnt(1)
	v_mfma_f32_32x32x16_bf16 v[112:127], v[160:163], v[64:67], v[96:111]
	ds_read_b128 v[160:163], v209 offset:32768
	ds_read_b128 v[226:229], v209 offset:36864
	ds_read_b128 v[238:241], v210 offset:36864
	ds_read_b128 v[182:185], v210 offset:32768
	ds_read_b128 v[242:245], v211 offset:36864
	ds_read_b128 v[188:191], v211 offset:32768
	v_exp_f32_e32 v186, v90
	v_exp_f32_e32 v187, v91
	s_andn2_b64 s[0:1], s[6:7], exec
	s_and_b64 s[6:7], s[8:9], exec
	s_or_b64 s[6:7], s[0:1], s[6:7]
	s_waitcnt lgkmcnt(5)
	v_mfma_f32_32x32x16_bf16 v[112:127], v[160:163], v[68:71], v[112:127]
	v_exp_f32_e32 v160, v80
	v_exp_f32_e32 v161, v81
	v_exp_f32_e32 v162, v82
	v_exp_f32_e32 v163, v83
	v_add_f32_e32 v80, v160, v165
	v_add_f32_e32 v80, v161, v80
	v_add_f32_e32 v165, v162, v80
	s_waitcnt lgkmcnt(2)
	v_mfma_f32_32x32x16_bf16 v[112:127], v[182:185], v[72:75], v[112:127]
	v_exp_f32_e32 v182, v86
	v_exp_f32_e32 v183, v87
	v_exp_f32_e32 v184, v88
	v_exp_f32_e32 v185, v89
	v_add_f32_e32 v165, v163, v165
	v_add_f32_e32 v165, v166, v165
	v_add_f32_e32 v165, v167, v165
	s_waitcnt lgkmcnt(0)
	v_mfma_f32_32x32x16_bf16 v[112:127], v[188:191], v[76:79], v[112:127]
	v_exp_f32_e32 v188, v92
	v_exp_f32_e32 v189, v93
	v_exp_f32_e32 v190, v94
	v_exp_f32_e32 v191, v95
	v_add_f32_e32 v165, v182, v165
	v_add_f32_e32 v165, v183, v165
	v_add_f32_e32 v165, v184, v165
	v_mfma_f32_32x32x16_bf16 v[80:95], v[222:225], v[64:67], v[96:111]
	v_add_f32_e32 v165, v185, v165
	v_add_f32_e32 v165, v186, v165
	v_add_f32_e32 v165, v187, v165
	v_add_f32_e32 v165, v188, v165
	v_add_f32_e32 v165, v189, v165
	v_add_f32_e32 v165, v190, v165
	v_add_f32_e32 v165, v191, v165
	v_mfma_f32_32x32x16_bf16 v[80:95], v[226:229], v[68:71], v[80:95]
	v_mov_b32_e32 v179, v165
	s_nop 1
	v_permlane32_swap_b32_e32 v165, v179
	v_add_f32_e64 v178, v164, v178
	v_add_f32_e64 v179, v165, v179
	v_cmp_ge_f32_e32 vcc, s99, v179
	s_cmp_eq_u64 vcc, exec
	v_mfma_f32_32x32x16_bf16 v[80:95], v[238:241], v[72:75], v[80:95]
	v_mfma_f32_32x32x16_bf16 v[80:95], v[242:245], v[76:79], v[80:95]
	s_cbranch_scc0 .LBB0_408

.LBB0_403:
	v_add_f32_e32 v178, v179, v178
	ds_read_b64_tr_b16 v[182:183], v202 offset:0
	ds_read_b64_tr_b16 v[184:185], v202 offset:0x800
	ds_read_b64_tr_b16 v[186:187], v202 offset:0x200
	ds_read_b64_tr_b16 v[188:189], v202 offset:0xa00
	ds_read_b64_tr_b16 v[214:215], v202 offset:0x400
	ds_read_b64_tr_b16 v[216:217], v202 offset:0xc00
	ds_read_b64_tr_b16 v[218:219], v202 offset:0x600
	ds_read_b64_tr_b16 v[220:221], v202 offset:0xe00
	ds_read_b64_tr_b16 v[222:223], v202 offset:0x1000
	ds_read_b64_tr_b16 v[224:225], v202 offset:0x1800
	ds_read_b64_tr_b16 v[226:227], v202 offset:0x1200
	ds_read_b64_tr_b16 v[228:229], v202 offset:0x1a00
	ds_read_b64_tr_b16 v[230:231], v202 offset:0x1400
	ds_read_b64_tr_b16 v[232:233], v202 offset:0x1c00
	ds_read_b64_tr_b16 v[234:235], v202 offset:0x1600
	ds_read_b64_tr_b16 v[236:237], v202 offset:0x1e00
	s_nop 0
	s_waitcnt lgkmcnt(8)
	v_exp_f32_e32 v112, v112
	v_mfma_f32_32x32x16_bf16 v[0:15], v[144:147], v[182:185], v[0:15]
	v_exp_f32_e32 v113, v113
	v_exp_f32_e32 v114, v114
	v_exp_f32_e32 v115, v115
	v_exp_f32_e32 v116, v116
	v_exp_f32_e32 v117, v117
	v_exp_f32_e32 v118, v118
	v_exp_f32_e32 v119, v119
	v_mfma_f32_32x32x16_bf16 v[48:63], v[144:147], v[186:189], v[48:63]
	v_exp_f32_e32 v120, v120
	v_exp_f32_e32 v121, v121
	v_exp_f32_e32 v122, v122
	v_exp_f32_e32 v123, v123
	v_exp_f32_e32 v124, v124
	v_exp_f32_e32 v125, v125
	v_exp_f32_e32 v126, v126
	v_mfma_f32_32x32x16_bf16 v[32:47], v[144:147], v[214:217], v[32:47]
	v_exp_f32_e32 v127, v127
	s_addk_i32 s51, 0x80
	s_add_i32 s50, s50, 2
	s_and_b64 vcc, exec, s[8:9]
	v_mfma_f32_32x32x16_bf16 v[16:31], v[144:147], v[218:221], v[16:31]
	ds_read_b64_tr_b16 v[144:145], v202 offset:0x2000
	ds_read_b64_tr_b16 v[146:147], v202 offset:0x2800
	ds_read_b64_tr_b16 v[182:183], v202 offset:0x2200
	ds_read_b64_tr_b16 v[184:185], v202 offset:0x2a00
	ds_read_b64_tr_b16 v[186:187], v202 offset:0x2400
	ds_read_b64_tr_b16 v[188:189], v202 offset:0x2c00
	ds_read_b64_tr_b16 v[214:215], v202 offset:0x2600
	ds_read_b64_tr_b16 v[216:217], v202 offset:0x2e00
	s_waitcnt lgkmcnt(8)
	ds_read_b64_tr_b16 v[218:219], v202 offset:0x3000
	ds_read_b64_tr_b16 v[220:221], v202 offset:0x3800
	s_nop 0
	v_mfma_f32_32x32x16_bf16 v[0:15], v[140:143], v[222:225], v[0:15]
	ds_read_b64_tr_b16 v[222:223], v202 offset:0x3200
	ds_read_b64_tr_b16 v[224:225], v202 offset:0x3a00
	v_mfma_f32_32x32x16_bf16 v[48:63], v[140:143], v[226:229], v[48:63]
	ds_read_b64_tr_b16 v[226:227], v202 offset:0x3400
	ds_read_b64_tr_b16 v[228:229], v202 offset:0x3c00
	v_mfma_f32_32x32x16_bf16 v[32:47], v[140:143], v[230:233], v[32:47]
	ds_read_b64_tr_b16 v[230:231], v202 offset:0x3600
	ds_read_b64_tr_b16 v[232:233], v202 offset:0x3e00
	s_waitcnt lgkmcnt(8)
	s_nop 0
	s_waitcnt lgkmcnt(0)
	v_mfma_f32_32x32x16_bf16 v[16:31], v[140:143], v[234:237], v[16:31]
	v_add_f32_e32 v140, v113, v112
	v_add_f32_e32 v140, v114, v140
	v_add_f32_e32 v140, v115, v140
	v_add_f32_e32 v140, v116, v140
	v_add_f32_e32 v140, v117, v140
	v_add_f32_e32 v140, v118, v140
	v_mfma_f32_32x32x16_bf16 v[0:15], v[164:167], v[144:147], v[0:15]
	v_add_f32_e32 v140, v119, v140
	v_add_f32_e32 v140, v120, v140
	v_add_f32_e32 v140, v121, v140
	v_add_f32_e32 v140, v122, v140
	v_add_f32_e32 v140, v123, v140
	v_add_f32_e32 v140, v124, v140
	v_add_f32_e32 v140, v125, v140
	v_mfma_f32_32x32x16_bf16 v[48:63], v[164:167], v[182:185], v[48:63]
	v_add_f32_e32 v140, v126, v140
	v_cvt_pk_bf16_f32 v144, v112, v113
	v_cvt_pk_bf16_f32 v145, v114, v115
	v_cvt_pk_bf16_f32 v146, v116, v117
	v_cvt_pk_bf16_f32 v147, v118, v119
	v_mfma_f32_32x32x16_bf16 v[32:47], v[164:167], v[186:189], v[32:47]
	v_mfma_f32_32x32x16_bf16 v[16:31], v[164:167], v[214:217], v[16:31]
	v_add_f32_e32 v164, v127, v140
	v_cvt_pk_bf16_f32 v140, v120, v121
	v_cvt_pk_bf16_f32 v141, v122, v123
	v_cvt_pk_bf16_f32 v142, v124, v125
	v_cvt_pk_bf16_f32 v143, v126, v127
	v_mfma_f32_32x32x16_bf16 v[0:15], v[160:163], v[218:221], v[0:15]
	v_add_u32_e32 v202, s100, v202
	v_add_u32_e32 v203, s100, v203
	s_sub_i32 s100, 0, s100
	s_sub_i32 s101, 0, s101
	s_waitcnt vmcnt(3)
	s_cbranch_vccz .Ldma_w3
	s_waitcnt vmcnt(0)
.Ldma_w3:
	s_waitcnt lgkmcnt(0)
	s_barrier
	v_mfma_f32_32x32x16_bf16 v[48:63], v[160:163], v[222:225], v[48:63]
	v_mfma_f32_32x32x16_bf16 v[32:47], v[160:163], v[226:229], v[32:47]
	v_mfma_f32_32x32x16_bf16 v[16:31], v[160:163], v[230:233], v[16:31]
	s_mov_b64 s[8:9], s[6:7]
	s_cbranch_vccz .LBB0_398
	s_branch .LBB0_411
